# mlstm_pre_unit: 16 loads per unit issued up front instead of load-wait-store per row piece
# baseline (speedup 1.0000x reference)
; __global__ void __launch_bounds__(512, 2) mk_fwd(Args a_) {
;     ...
;             for (int ui = bid; ui < 1024; ui += G) mlstm_pre_unit(lds, tid, ui, z1, ws, MK_DUPS != 3 || rep == 1);
.LBB0_109:
	s_mov_b32 s8, s34
	s_branch .LBB0_111
	s_nop 0
	s_nop 0
	s_nop 0
	s_nop 0
	s_nop 0
	s_nop 0
	s_nop 0
	s_nop 0
	s_nop 0
	s_nop 0
	s_nop 0
	s_nop 0
	s_nop 0
	s_nop 0
	s_nop 0
	s_nop 0
	s_nop 0
	s_nop 0
	s_nop 0
	s_nop 0
	s_nop 0
	s_nop 0
	s_nop 0
	s_nop 0
	s_nop 0
	s_nop 0
	s_nop 0
	s_nop 0
	s_nop 0
	s_nop 0
	s_nop 0
	s_nop 0
	s_nop 0
	s_nop 0
	s_nop 0
	s_nop 0
	s_nop 0
	s_nop 0
	s_nop 0
	s_nop 0
	s_nop 0
	s_nop 0
	s_nop 0
	s_nop 0
	s_nop 0
	s_nop 0
	s_nop 0
	s_nop 0
	s_nop 0
	s_nop 0
	s_nop 0
	s_nop 0
	s_nop 0
	s_nop 0
	s_nop 0
	s_nop 0
	s_nop 0
	s_nop 0
	s_nop 0
	s_nop 0
	s_nop 0
	s_nop 0
	s_nop 0
	s_nop 0
	s_nop 0
	s_nop 0
	s_nop 0
	s_nop 0
	s_nop 0
	s_nop 0
	s_nop 0
	s_nop 0
	s_nop 0
	s_nop 0
	s_nop 0
	s_nop 0
	s_nop 0
	s_nop 0
	s_nop 0
	s_nop 0
	s_nop 0
	s_nop 0
	s_nop 0
	s_nop 0
	s_nop 0
	s_nop 0
	s_nop 0
	s_nop 0
	s_nop 0
	s_nop 0
	s_nop 0
	s_nop 0
	s_nop 0
	s_nop 0
	s_nop 0
	s_nop 0
	s_nop 0
	s_nop 0
	s_nop 0
	s_nop 0
	s_nop 0
	s_nop 0
	s_nop 0
	s_nop 0
	s_nop 0
	s_nop 0
	s_nop 0
	s_nop 0
	s_nop 0
	s_nop 0
	s_nop 0
	s_nop 0
	s_nop 0
	s_nop 0
	s_nop 0
	s_nop 0
	s_nop 0
	s_nop 0
	s_nop 0
	s_nop 0
	s_nop 0
	s_nop 0
	s_nop 0
	s_nop 0
	s_nop 0
	s_nop 0
	s_nop 0
	s_nop 0
	s_nop 0
	s_nop 0
	s_nop 0
	s_nop 0
	s_nop 0
	s_nop 0
	s_nop 0
	s_nop 0
	s_nop 0
	s_nop 0
	s_nop 0
	s_nop 0
	s_nop 0
	s_nop 0
	s_nop 0
	s_nop 0
	s_nop 0
	s_nop 0
	s_nop 0
	s_nop 0
	s_nop 0
	s_nop 0
	s_nop 0
	s_nop 0
	s_nop 0
	s_nop 0
	s_nop 0
	s_nop 0
	s_nop 0
	s_nop 0
	s_nop 0
	s_nop 0
	s_nop 0
	s_nop 0
	s_nop 0
	s_nop 0
	s_nop 0
	s_nop 0
	s_nop 0
	s_nop 0
	s_nop 0
	s_nop 0
	s_nop 0
	s_nop 0
	s_nop 0
	s_nop 0
	s_nop 0
	s_nop 0
	s_nop 0
	s_nop 0
	s_nop 0
	s_nop 0
	s_nop 0
	s_nop 0
	s_nop 0
	s_nop 0
	s_nop 0
	s_nop 0
	s_nop 0
	s_nop 0
	s_nop 0
	s_nop 0
	s_nop 0
	s_nop 0
	s_nop 0
	s_nop 0
	s_nop 0
	s_nop 0
	s_nop 0
	s_nop 0
	s_nop 0
	s_nop 0
	s_nop 0
	s_nop 0
	s_nop 0
	s_nop 0
	s_nop 0
	s_nop 0
	s_nop 0
	s_nop 0
	s_nop 0
	s_nop 0
	s_nop 0
	s_nop 0
	s_nop 0
	s_nop 0
	s_nop 0
	s_nop 0
	s_nop 0
	s_nop 0
	s_nop 0
	s_nop 0
	s_nop 0
	s_nop 0
	s_nop 0
	s_nop 0
	s_nop 0
	s_nop 0
	s_nop 0
	s_nop 0
	s_nop 0
	s_nop 0
	s_nop 0
	s_nop 0
	s_nop 0
	s_nop 0
	s_nop 0
	s_nop 0
	s_nop 0
	s_nop 0
	s_nop 0
	s_nop 0
	s_nop 0
	s_nop 0
	s_nop 0
	s_nop 0
	s_nop 0
	s_nop 0
	s_nop 0
	s_nop 0
	s_nop 0
	s_nop 0
	s_nop 0
	s_nop 0
	s_nop 0
	s_nop 0
	s_nop 0
	s_nop 0
	s_nop 0
	s_nop 0
	s_nop 0
	s_nop 0
	s_nop 0
	s_nop 0
	s_nop 0
	s_nop 0
	s_nop 0
	s_nop 0
	s_nop 0
	s_nop 0
	s_nop 0
	s_nop 0
	s_nop 0
	s_nop 0
	s_nop 0
	s_nop 0
	s_nop 0
	s_nop 0
	s_nop 0
	s_nop 0
	s_nop 0
	s_nop 0
	s_nop 0
	s_nop 0
	s_nop 0
	s_nop 0
	s_nop 0
	s_nop 0
	s_nop 0
	s_nop 0
	s_nop 0
	s_nop 0
	s_nop 0
	s_nop 0
	s_nop 0
	s_nop 0
	s_nop 0
	s_nop 0
	s_nop 0
	s_nop 0
	s_nop 0
	s_nop 0
	s_nop 0
	s_nop 0
	s_nop 0
	s_nop 0
	s_nop 0
	s_nop 0
	s_nop 0
	s_nop 0
	s_nop 0
	s_nop 0
	s_nop 0
	s_nop 0
	s_nop 0
	s_nop 0
	s_nop 0
	s_nop 0
	s_nop 0
	s_nop 0
	s_nop 0
	s_nop 0
	s_nop 0
	s_nop 0
	s_nop 0
	s_nop 0
	s_nop 0
	s_nop 0
	s_nop 0
	s_nop 0
	s_nop 0
	s_nop 0
	s_nop 0
	s_nop 0
	s_nop 0
	s_nop 0
	s_nop 0
	s_nop 0
	s_nop 0
	s_nop 0
	s_nop 0
	s_nop 0
	s_nop 0
	s_nop 0
	s_nop 0
	s_nop 0
	s_nop 0
	s_nop 0
	s_nop 0
	s_nop 0
	s_nop 0
	s_nop 0
	s_nop 0
	s_nop 0
	s_nop 0
	s_nop 0
	s_nop 0
	s_nop 0
	s_nop 0
	s_nop 0
	s_nop 0
	s_nop 0
	s_nop 0
	s_nop 0
	s_nop 0
	s_nop 0
	s_nop 0
	s_nop 0
	s_nop 0
	s_nop 0
	s_nop 0

; #define LAS __attribute__((address_space(3)))
; __device__ __forceinline__ u32x4 pack8(const float (&f)[8]) { u32x4 w; w.x = pk2(f[0], f[1]); w.y = pk2(f[2], f[3]); w.z = pk2(f[4], f[5]); w.w = pk2(f[6], f[7]); return w; }
; __device__ __forceinline__ void mlstm_pre_unit(LAS unsigned char* lds_wg, int tid_in, int pair, bf16_t* z1, unsigned char* ws, bool st = true) {
;     ...
;     if (w4 == 0) { A_[lane] = ((const float*)(ws + GV_A))[(tok0 + lane) * 8 + h]; R_[lane] = ((const float*)(ws + GV_R))[(tok0 + lane) * 8 + h]; }
; #pragma unroll
;     for (int i = 0; i < 8; ++i) {
;         const int row = (t256 >> 5) + 8 * i, cgi = t256 & 31, isk = cgi >> 4, c8 = (cgi & 15) * 8;
;         bf16_t* gp = z1 + (tok0 + row) * Z1_LD + 1280 + isk * 1024 + h * 128 + c8;
;         const u32x4 v = *(const u32x4*)gp;
;         if (!isk) { *(LAS u32x4*)(Qb + row * QS + c8 * 2) = v; const float wis = ((const float*)(ws + GV_WI))[(tok0 + row) * 8 + h]; float f[8]; unpack8(v, f);
; #pragma unroll
;             for (int e = 0; e < 8; ++e) f[e] *= wis;
;             if (st) *(u32x4*)gp = pack8(f); }
;         else { *(LAS u32x4*)(Kb + row * QS + c8 * 2) = v; const float us = Ug[(tok0 + row) * 8 + h]; float f[8]; unpack8(v, f);
; #pragma unroll
;             for (int e = 0; e < 8; ++e) f[e] *= us;
;             const u32x4 w = pack8(f); *(LAS u32x4*)(KUb + row * QS + c8 * 2) = w; if (st) *(u32x4*)gp = w; }
;     }
.LBB0_115:
	s_lshl_b32 s14, s27, 2
	v_readlane_b32 s18, v254, 22
	v_readlane_b32 s19, v254, 23
	s_add_u32 s22, s18, s14
	s_addc_u32 s23, s19, 0
	v_readlane_b32 s18, v254, 28
	v_readlane_b32 s19, v254, 29
	s_add_u32 s20, s18, s14
	s_addc_u32 s21, s19, 0
	v_readlane_b32 s18, v254, 5
	v_bfe_u32 v17, v18, 5, 3
	v_readlane_b32 s19, v254, 6
	v_lshlrev_b32_e32 v0, 3, v18
	v_or_b32_e32 v2, s9, v17
	v_mov_b64_e32 v[4:5], s[18:19]
	v_bfe_u32 v20, v18, 4, 1
	v_and_b32_e32 v0, 0x78, v0
	s_mul_i32 s29, s15, 0x1a00
	v_mad_u64_u32 v[4:5], s[18:19], v2, s69, v[4:5]
	v_lshlrev_b32_e32 v10, 1, v0
	v_add_u32_e32 v5, s29, v5
	v_lshlrev_b32_e32 v0, 11, v20
	v_lshl_add_u64 v[4:5], v[4:5], 0, v[0:1]
	s_lshl_b32 s38, s27, 8
	v_lshl_add_u64 v[4:5], v[4:5], 0, s[38:39]
	v_mov_b32_e32 v11, v1
	v_lshl_add_u64 v[12:13], v[4:5], 0, v[10:11]
	v_mov_b64_e32 v[72:73], v[12:13]
	s_mov_b64 s[18:19], 0xd000
	v_lshl_add_u64 v[74:75], v[72:73], 0, s[18:19]
	v_lshl_add_u64 v[76:77], v[74:75], 0, s[18:19]
	v_lshl_add_u64 v[78:79], v[76:77], 0, s[18:19]
	v_lshl_add_u64 v[80:81], v[78:79], 0, s[18:19]
	v_lshl_add_u64 v[82:83], v[80:81], 0, s[18:19]
	v_lshl_add_u64 v[84:85], v[82:83], 0, s[18:19]
	v_lshl_add_u64 v[86:87], v[84:85], 0, s[18:19]
	global_load_dwordx4 v[40:43], v[72:73], off offset:2560
	global_load_dwordx4 v[44:47], v[74:75], off offset:2560
	global_load_dwordx4 v[48:51], v[76:77], off offset:2560
	global_load_dwordx4 v[52:55], v[78:79], off offset:2560
	global_load_dwordx4 v[56:59], v[80:81], off offset:2560
	global_load_dwordx4 v[60:63], v[82:83], off offset:2560
	global_load_dwordx4 v[64:67], v[84:85], off offset:2560
	global_load_dwordx4 v[68:71], v[86:87], off offset:2560
	v_mov_b32_e32 v3, s15
	v_and_b32_e32 v0, 16, v18
	v_mul_u32_u24_e32 v4, 0x110, v17
	v_lshlrev_b64 v[14:15], 5, v[2:3]
	v_add_u32_e32 v2, s24, v10
	v_cmp_ne_u32_e32 vcc, 0, v0
	v_add_u32_e32 v16, v2, v4
	v_mov_b32_e32 v2, s20
	v_mov_b32_e32 v3, s21
	v_mov_b32_e32 v4, s22
	v_mov_b32_e32 v5, s23
	v_add_u32_e32 v6, 0x4400, v16
	v_cndmask_b32_e32 v2, v2, v4, vcc
	v_cndmask_b32_e32 v3, v3, v5, vcc
	v_cndmask_b32_e32 v100, v16, v6, vcc
	v_lshl_add_u64 v[98:99], v[2:3], 0, v[14:15]
	global_load_dword v88, v[98:99], off
	global_load_dword v89, v[98:99], off offset:256
	global_load_dword v90, v[98:99], off offset:512
	global_load_dword v91, v[98:99], off offset:768
	global_load_dword v92, v[98:99], off offset:1024
	global_load_dword v93, v[98:99], off offset:1280
	global_load_dword v94, v[98:99], off offset:1536
	global_load_dword v95, v[98:99], off offset:1792
	s_waitcnt vmcnt(7)
	ds_write_b128 v100, v[40:43]
	v_lshlrev_b32_e32 v2, 16, v40
	v_and_b32_e32 v3, 0xffff0000, v40
	v_lshlrev_b32_e32 v4, 16, v41
	v_and_b32_e32 v5, 0xffff0000, v41
	v_lshlrev_b32_e32 v6, 16, v42
	v_and_b32_e32 v7, 0xffff0000, v42
	v_lshlrev_b32_e32 v8, 16, v43
	v_and_b32_e32 v9, 0xffff0000, v43
	v_mul_f32_e32 v2, v88, v2
	v_mul_f32_e32 v3, v88, v3
	v_mul_f32_e32 v4, v88, v4
	v_mul_f32_e32 v5, v88, v5
	v_mul_f32_e32 v6, v88, v6
	v_mul_f32_e32 v7, v88, v7
	v_mul_f32_e32 v8, v88, v8
	v_mul_f32_e32 v9, v88, v9
	v_cvt_pk_bf16_f32 v104, v2, v3
	v_cvt_pk_bf16_f32 v105, v4, v5
	v_cvt_pk_bf16_f32 v106, v6, v7
	v_cvt_pk_bf16_f32 v107, v8, v9
	global_store_dwordx4 v[72:73], v[104:107], off offset:2560
	s_waitcnt vmcnt(7)
	ds_write_b128 v100, v[44:47] offset:2176
	v_lshlrev_b32_e32 v2, 16, v44
	v_and_b32_e32 v3, 0xffff0000, v44
	v_lshlrev_b32_e32 v4, 16, v45
	v_and_b32_e32 v5, 0xffff0000, v45
	v_lshlrev_b32_e32 v6, 16, v46
	v_and_b32_e32 v7, 0xffff0000, v46
	v_lshlrev_b32_e32 v8, 16, v47
	v_and_b32_e32 v9, 0xffff0000, v47
	v_mul_f32_e32 v2, v89, v2
	v_mul_f32_e32 v3, v89, v3
	v_mul_f32_e32 v4, v89, v4
	v_mul_f32_e32 v5, v89, v5
	v_mul_f32_e32 v6, v89, v6
	v_mul_f32_e32 v7, v89, v7
	v_mul_f32_e32 v8, v89, v8
	v_mul_f32_e32 v9, v89, v9
	v_cvt_pk_bf16_f32 v108, v2, v3
	v_cvt_pk_bf16_f32 v109, v4, v5
	v_cvt_pk_bf16_f32 v110, v6, v7
	v_cvt_pk_bf16_f32 v111, v8, v9
	global_store_dwordx4 v[74:75], v[108:111], off offset:2560
	s_waitcnt vmcnt(7)
	ds_write_b128 v100, v[48:51] offset:4352
	v_lshlrev_b32_e32 v2, 16, v48
	v_and_b32_e32 v3, 0xffff0000, v48
	v_lshlrev_b32_e32 v4, 16, v49
	v_and_b32_e32 v5, 0xffff0000, v49
	v_lshlrev_b32_e32 v6, 16, v50
	v_and_b32_e32 v7, 0xffff0000, v50
	v_lshlrev_b32_e32 v8, 16, v51
	v_and_b32_e32 v9, 0xffff0000, v51
	v_mul_f32_e32 v2, v90, v2
	v_mul_f32_e32 v3, v90, v3
	v_mul_f32_e32 v4, v90, v4
	v_mul_f32_e32 v5, v90, v5
	v_mul_f32_e32 v6, v90, v6
	v_mul_f32_e32 v7, v90, v7
	v_mul_f32_e32 v8, v90, v8
	v_mul_f32_e32 v9, v90, v9
	v_cvt_pk_bf16_f32 v112, v2, v3
	v_cvt_pk_bf16_f32 v113, v4, v5
	v_cvt_pk_bf16_f32 v114, v6, v7
	v_cvt_pk_bf16_f32 v115, v8, v9
	global_store_dwordx4 v[76:77], v[112:115], off offset:2560
	s_waitcnt vmcnt(7)
	ds_write_b128 v100, v[52:55] offset:6528
	v_lshlrev_b32_e32 v2, 16, v52
	v_and_b32_e32 v3, 0xffff0000, v52
	v_lshlrev_b32_e32 v4, 16, v53
	v_and_b32_e32 v5, 0xffff0000, v53
	v_lshlrev_b32_e32 v6, 16, v54
	v_and_b32_e32 v7, 0xffff0000, v54
	v_lshlrev_b32_e32 v8, 16, v55
	v_and_b32_e32 v9, 0xffff0000, v55
	v_mul_f32_e32 v2, v91, v2
	v_mul_f32_e32 v3, v91, v3
	v_mul_f32_e32 v4, v91, v4
	v_mul_f32_e32 v5, v91, v5
	v_mul_f32_e32 v6, v91, v6
	v_mul_f32_e32 v7, v91, v7
	v_mul_f32_e32 v8, v91, v8
	v_mul_f32_e32 v9, v91, v9
	v_cvt_pk_bf16_f32 v116, v2, v3
	v_cvt_pk_bf16_f32 v117, v4, v5
	v_cvt_pk_bf16_f32 v118, v6, v7
	v_cvt_pk_bf16_f32 v119, v8, v9
	global_store_dwordx4 v[78:79], v[116:119], off offset:2560
	s_waitcnt vmcnt(7)
; #define LAS __attribute__((address_space(3)))
; __device__ __forceinline__ u32x4 pack8(const float (&f)[8]) { u32x4 w; w.x = pk2(f[0], f[1]); w.y = pk2(f[2], f[3]); w.z = pk2(f[4], f[5]); w.w = pk2(f[6], f[7]); return w; }
; #define MFMA32(a, b, c) __builtin_amdgcn_mfma_f32_32x32x16_bf16((a), (b), (c), 0, 0, 0)
; __device__ __forceinline__ void mlstm_pre_unit(LAS unsigned char* lds_wg, int tid_in, int pair, bf16_t* z1, unsigned char* ws, bool st = true) {
;     ...
;     for (int i = 0; i < 8; ++i) {
;         const int row = (t256 >> 5) + 8 * i, cgi = t256 & 31, isk = cgi >> 4, c8 = (cgi & 15) * 8;
;         bf16_t* gp = z1 + (tok0 + row) * Z1_LD + 1280 + isk * 1024 + h * 128 + c8;
;         const u32x4 v = *(const u32x4*)gp;
;         if (!isk) { *(LAS u32x4*)(Qb + row * QS + c8 * 2) = v; const float wis = ((const float*)(ws + GV_WI))[(tok0 + row) * 8 + h]; float f[8]; unpack8(v, f);
; #pragma unroll
;             for (int e = 0; e < 8; ++e) f[e] *= wis;
;             if (st) *(u32x4*)gp = pack8(f); }
;         else { *(LAS u32x4*)(Kb + row * QS + c8 * 2) = v; const float us = Ug[(tok0 + row) * 8 + h]; float f[8]; unpack8(v, f);
; #pragma unroll
;             for (int e = 0; e < 8; ++e) f[e] *= us;
;             const u32x4 w = pack8(f); *(LAS u32x4*)(KUb + row * QS + c8 * 2) = w; if (st) *(u32x4*)gp = w; }
;     }
;     ...
;     if (w4 < 3) {
;         const int tb = w4 >= 1, sb = w4 == 2;
;         f32x16 sa;
; #pragma unroll
;         for (int i = 0; i < 16; ++i) sa[i] = 0.f;
; #pragma unroll
;         for (int ks = 0; ks < 8; ++ks) {
;             const bf16x8 qa = *(const LAS bf16x8*)(Qb + (32 * tb + r) * QS + ks * 32 + hh * 16);
;             const bf16x8 kb = *(const LAS bf16x8*)(Kb + (32 * sb + r) * QS + ks * 32 + hh * 16);
;             sa = MFMA32(qa, kb, sa);
;         }
;         const int s = 32 * sb + r; const float as = A_[s];
; #pragma unroll
;         for (int i = 0; i < 16; ++i) {
;             const int t = 32 * tb + (i & 3) + 8 * (i >> 2) + 4 * hh;
;             const float w = (s <= t) ? __expf(as + R_[t]) : 0.f;
	ds_write_b128 v100, v[56:59] offset:8704
	v_lshlrev_b32_e32 v2, 16, v56
	v_and_b32_e32 v3, 0xffff0000, v56
	v_lshlrev_b32_e32 v4, 16, v57
	v_and_b32_e32 v5, 0xffff0000, v57
	v_lshlrev_b32_e32 v6, 16, v58
	v_and_b32_e32 v7, 0xffff0000, v58
	v_lshlrev_b32_e32 v8, 16, v59
	v_and_b32_e32 v9, 0xffff0000, v59
	v_mul_f32_e32 v2, v92, v2
	v_mul_f32_e32 v3, v92, v3
	v_mul_f32_e32 v4, v92, v4
	v_mul_f32_e32 v5, v92, v5
	v_mul_f32_e32 v6, v92, v6
	v_mul_f32_e32 v7, v92, v7
	v_mul_f32_e32 v8, v92, v8
	v_mul_f32_e32 v9, v92, v9
	v_cvt_pk_bf16_f32 v120, v2, v3
	v_cvt_pk_bf16_f32 v121, v4, v5
	v_cvt_pk_bf16_f32 v122, v6, v7
	v_cvt_pk_bf16_f32 v123, v8, v9
	global_store_dwordx4 v[80:81], v[120:123], off offset:2560
	s_waitcnt vmcnt(7)
	ds_write_b128 v100, v[60:63] offset:10880
	v_lshlrev_b32_e32 v2, 16, v60
	v_and_b32_e32 v3, 0xffff0000, v60
	v_lshlrev_b32_e32 v4, 16, v61
	v_and_b32_e32 v5, 0xffff0000, v61
	v_lshlrev_b32_e32 v6, 16, v62
	v_and_b32_e32 v7, 0xffff0000, v62
	v_lshlrev_b32_e32 v8, 16, v63
	v_and_b32_e32 v9, 0xffff0000, v63
	v_mul_f32_e32 v2, v93, v2
	v_mul_f32_e32 v3, v93, v3
	v_mul_f32_e32 v4, v93, v4
	v_mul_f32_e32 v5, v93, v5
	v_mul_f32_e32 v6, v93, v6
	v_mul_f32_e32 v7, v93, v7
	v_mul_f32_e32 v8, v93, v8
	v_mul_f32_e32 v9, v93, v9
	v_cvt_pk_bf16_f32 v124, v2, v3
	v_cvt_pk_bf16_f32 v125, v4, v5
	v_cvt_pk_bf16_f32 v126, v6, v7
	v_cvt_pk_bf16_f32 v127, v8, v9
	global_store_dwordx4 v[82:83], v[124:127], off offset:2560
	s_waitcnt vmcnt(7)
	ds_write_b128 v100, v[64:67] offset:13056
	v_lshlrev_b32_e32 v2, 16, v64
	v_and_b32_e32 v3, 0xffff0000, v64
	v_lshlrev_b32_e32 v4, 16, v65
	v_and_b32_e32 v5, 0xffff0000, v65
	v_lshlrev_b32_e32 v6, 16, v66
	v_and_b32_e32 v7, 0xffff0000, v66
	v_lshlrev_b32_e32 v8, 16, v67
	v_and_b32_e32 v9, 0xffff0000, v67
	v_mul_f32_e32 v2, v94, v2
	v_mul_f32_e32 v3, v94, v3
	v_mul_f32_e32 v4, v94, v4
	v_mul_f32_e32 v5, v94, v5
	v_mul_f32_e32 v6, v94, v6
	v_mul_f32_e32 v7, v94, v7
	v_mul_f32_e32 v8, v94, v8
	v_mul_f32_e32 v9, v94, v9
	v_cvt_pk_bf16_f32 v128, v2, v3
	v_cvt_pk_bf16_f32 v129, v4, v5
	v_cvt_pk_bf16_f32 v130, v6, v7
	v_cvt_pk_bf16_f32 v131, v8, v9
	global_store_dwordx4 v[84:85], v[128:131], off offset:2560
	s_waitcnt vmcnt(7)
	ds_write_b128 v100, v[68:71] offset:15232
	v_lshlrev_b32_e32 v2, 16, v68
	v_and_b32_e32 v3, 0xffff0000, v68
	v_lshlrev_b32_e32 v4, 16, v69
	v_and_b32_e32 v5, 0xffff0000, v69
	v_lshlrev_b32_e32 v6, 16, v70
	v_and_b32_e32 v7, 0xffff0000, v70
	v_lshlrev_b32_e32 v8, 16, v71
	v_and_b32_e32 v9, 0xffff0000, v71
	v_mul_f32_e32 v2, v95, v2
	v_mul_f32_e32 v3, v95, v3
	v_mul_f32_e32 v4, v95, v4
	v_mul_f32_e32 v5, v95, v5
	v_mul_f32_e32 v6, v95, v6
	v_mul_f32_e32 v7, v95, v7
	v_mul_f32_e32 v8, v95, v8
	v_mul_f32_e32 v9, v95, v9
	v_cvt_pk_bf16_f32 v132, v2, v3
	v_cvt_pk_bf16_f32 v133, v4, v5
	v_cvt_pk_bf16_f32 v134, v6, v7
	v_cvt_pk_bf16_f32 v135, v8, v9
	global_store_dwordx4 v[86:87], v[132:135], off offset:2560
	s_mov_b64 s[18:19], exec
	s_and_b64 exec, exec, vcc
	ds_write_b128 v16, v[104:107] offset:34816
	ds_write_b128 v16, v[108:111] offset:36992
	ds_write_b128 v16, v[112:115] offset:39168
	ds_write_b128 v16, v[116:119] offset:41344
	ds_write_b128 v16, v[120:123] offset:43520
	ds_write_b128 v16, v[124:127] offset:45696
	ds_write_b128 v16, v[128:131] offset:47872
	ds_write_b128 v16, v[132:135] offset:50048
	s_mov_b64 exec, s[18:19]
	s_and_b32 s18, s26, 0xfffffe00
	s_lshl_b32 s19, s27, 6
	s_or_b32 s18, s19, s18
	s_or_b32 s20, s18, s28
	s_cmp_eq_u32 s25, 3
	s_mov_b64 s[18:19], -1
	s_waitcnt lgkmcnt(0)
	s_barrier
	s_cbranch_scc1 .LBB0_213
	s_and_b64 s[18:19], exec, s[16:17]
	v_and_b32_e32 v22, 31, v18
	s_cselect_b32 s18, 0, 32
	v_lshrrev_b32_e32 v21, 5, v19
	v_or_b32_e32 v0, s18, v22
	v_mul_u32_u24_e32 v0, 0x110, v0
	v_lshlrev_b32_e32 v6, 4, v21
	s_cmp_eq_u32 s25, 2
	v_add3_u32 v20, s24, v0, v6
	s_cselect_b32 s19, 32, 0
	ds_read_b128 v[2:5], v20
	v_or_b32_e32 v0, s19, v22
	v_mov_b32_e32 v7, s24
	v_mad_u32_u24 v23, v0, s72, v7
	v_add_u32_e32 v32, v23, v6
	ds_read_b128 v[6:9], v32 offset:17408
	s_waitcnt lgkmcnt(0)
	v_mfma_f32_32x32x16_bf16 v[2:17], v[2:5], v[6:9], 0
	ds_read_b128 v[24:27], v20 offset:32
	ds_read_b128 v[28:31], v32 offset:17440
	s_movk_i32 s19, 0xfef4
	v_lshl_or_b32 v21, v21, 2, s18
	v_cmp_le_u32_e32 vcc, v0, v21
	s_waitcnt lgkmcnt(0)
	v_mfma_f32_32x32x16_bf16 v[2:17], v[24:27], v[28:31], v[2:17]
	ds_read_b128 v[24:27], v20 offset:64
	ds_read_b128 v[28:31], v32 offset:17472
	s_waitcnt lgkmcnt(0)
	v_mfma_f32_32x32x16_bf16 v[2:17], v[24:27], v[28:31], v[2:17]
	ds_read_b128 v[24:27], v20 offset:96
	ds_read_b128 v[28:31], v32 offset:17504
	s_waitcnt lgkmcnt(0)
	v_mfma_f32_32x32x16_bf16 v[2:17], v[24:27], v[28:31], v[2:17]
	ds_read_b128 v[24:27], v20 offset:128
	ds_read_b128 v[28:31], v32 offset:17536
	s_waitcnt lgkmcnt(0)
	v_mfma_f32_32x32x16_bf16 v[2:17], v[24:27], v[28:31], v[2:17]
	ds_read_b128 v[24:27], v20 offset:160
	ds_read_b128 v[28:31], v32 offset:17568
	s_waitcnt lgkmcnt(0)
	v_mfma_f32_32x32x16_bf16 v[2:17], v[24:27], v[28:31], v[2:17]
	ds_read_b128 v[24:27], v20 offset:192
	ds_read_b128 v[28:31], v32 offset:17600
	s_waitcnt lgkmcnt(0)
	v_mfma_f32_32x32x16_bf16 v[2:17], v[24:27], v[28:31], v[2:17]
	ds_read_b128 v[24:27], v20 offset:224
	ds_read_b128 v[28:31], v32 offset:17632
	v_mad_i32_i24 v20, v0, s19, v23
	ds_read_b32 v20, v20 offset:61440
	s_waitcnt lgkmcnt(1)
	v_mfma_f32_32x32x16_bf16 v[2:17], v[24:27], v[28:31], v[2:17]
	v_mov_b32_e32 v24, 0
	s_and_saveexec_b64 s[18:19], vcc
	s_cbranch_execz .LBB0_150
	v_lshl_add_u32 v23, v21, 2, s24
	ds_read_b32 v23, v23 offset:61696
	s_waitcnt lgkmcnt(0)
	v_add_f32_e32 v23, v20, v23
	v_mul_f32_e32 v23, 0x3fb8aa3b, v23
	v_exp_f32_e32 v24, v23
